# head 0 ranking also via DPP bitonic sort; parity masks in s[50:53] set once per phase
# speedup vs baseline: 1.0081x; 1.0011x over previous
.LBB0_324:
	s_nop 0
	v_readlane_b32 s0, v249, 46
	v_readlane_b32 s1, v249, 47
	s_and_b64 vcc, exec, s[0:1]
	s_cbranch_vccz .LBB0_345
	v_mov_b32_e32 v1, v220
	v_readlane_b32 s0, v249, 0
	s_nop 0
	v_ashrrev_i32_e32 v0, 6, v1
	v_lshl_add_u32 v116, s0, 2, v0
	s_movk_i32 s0, 0x4200
	v_cmp_gt_i32_e32 vcc, s0, v116
	s_and_saveexec_b64 s[0:1], vcc
	s_cbranch_execz .LBB0_344
	v_readlane_b32 s2, v249, 37
	v_readlane_b32 s26, v249, 30
	v_readlane_b32 s3, v249, 38
	v_readlane_b32 s27, v249, 31
	s_mul_hi_i32 s4, s2, 0x1400000
	s_mul_i32 s5, s2, 0x1400000
	s_load_dwordx2 s[2:3], s[26:27], 0x160
	v_and_b32_e32 v6, 31, v1
	v_mul_u32_u24_e32 v2, 24, v6
	v_mov_b32_e32 v3, v80
	v_and_b32_e32 v81, 63, v1
	v_and_b32_e32 v255, 32, v81
	v_lshlrev_b32_e32 v255, 2, v255
	s_mov_b32 s50, 0x55555555
	s_mov_b32 s51, 0x55555555
	s_mov_b32 s52, 0x33333333
	s_mov_b32 s53, 0x33333333
	s_waitcnt lgkmcnt(0)
	s_add_u32 s2, s2, s5
	s_addc_u32 s3, s3, s4
	v_lshl_add_u64 v[118:119], s[2:3], 0, v[2:3]
	v_lshlrev_b32_e32 v2, 4, v6
	s_getpc_b64 s[4:5]
	s_add_u32 s4, s4, c_cand@rel32@lo+4
	s_addc_u32 s5, s5, c_cand@rel32@hi+12
	v_lshl_add_u64 v[120:121], s[2:3], 0, v[2:3]
	s_load_dwordx4 s[12:15], s[26:27], 0x90
	s_load_dwordx2 s[2:3], s[26:27], 0xc8
	global_load_ubyte v2, v81, s[4:5]
	v_readlane_b32 s16, v249, 13
	s_sub_i32 s10, s16, 19
	s_cmp_lt_u32 s10, 6
	s_cselect_b64 s[4:5], -1, 0
	s_cmp_gt_u32 s10, 5
	v_readlane_b32 s10, v249, 39
	v_readlane_b32 s11, v249, 40
	s_cselect_b64 s[20:21], -1, 0
	s_lshl_b64 s[10:11], s[10:11], 2
	s_waitcnt lgkmcnt(0)
	s_add_u32 s22, s14, s10
	s_addc_u32 s23, s15, s11
	s_add_u32 s24, s12, s10
	s_addc_u32 s25, s13, s11
	s_load_dwordx2 s[10:11], s[26:27], 0x140
	v_lshlrev_b32_e32 v3, 3, v81
	v_lshlrev_b32_e32 v4, 6, v6
	v_mov_b32_e32 v5, v80
	v_lshl_or_b32 v239, v0, 12, v3
	s_waitcnt lgkmcnt(0)
	v_lshl_add_u64 v[122:123], s[10:11], 0, v[4:5]
	v_and_b32_e32 v3, 3, v1
	v_and_b32_e32 v4, 64, v229
	v_cmp_eq_u32_e64 s[12:13], 0, v3
	v_xor_b32_e32 v3, 4, v229
	v_add_u32_e32 v4, 64, v4
	v_cmp_lt_i32_e32 vcc, v3, v4
	v_readlane_b32 s18, v249, 15
	v_readlane_b32 s19, v249, 16
	v_cndmask_b32_e32 v3, v229, v3, vcc
	v_lshlrev_b32_e32 v240, 2, v3
	v_xor_b32_e32 v3, 8, v229
	v_cmp_lt_i32_e32 vcc, v3, v4
	v_readlane_b32 s17, v249, 14
	v_cmp_lt_u32_e64 s[6:7], 31, v81
	v_cndmask_b32_e32 v3, v229, v3, vcc
	v_lshlrev_b32_e32 v241, 2, v3
	v_xor_b32_e32 v3, 16, v229
	v_cmp_lt_i32_e32 vcc, v3, v4
	v_cmp_gt_u32_e64 s[8:9], 32, v81
	v_cmp_gt_u32_e64 s[10:11], 50, v81
	v_cndmask_b32_e32 v3, v229, v3, vcc
	v_lshlrev_b32_e32 v242, 2, v3
	v_xor_b32_e32 v3, 32, v229
	v_cmp_lt_i32_e32 vcc, v3, v4
	s_waitcnt vmcnt(0)
	v_and_b32_e32 v0, 15, v2
	v_cndmask_b32_e32 v3, v229, v3, vcc
	v_lshlrev_b32_e32 v243, 2, v3
	v_and_b32_e32 v3, 16, v1
	v_cmp_eq_u32_e64 s[14:15], 0, v3
	v_and_b32_e32 v3, 8, v1
	v_and_b32_e32 v1, 4, v1
	v_cmp_eq_u32_e64 s[18:19], 0, v1
	v_xor_b32_e32 v1, 2, v229
	v_cmp_lt_i32_e32 vcc, v1, v4
	v_lshrrev_b32_e32 v2, 4, v2
	v_cmp_eq_u32_e64 s[16:17], 0, v3
	v_cndmask_b32_e32 v1, v229, v1, vcc
	v_lshlrev_b32_e32 v244, 2, v1
	v_xor_b32_e32 v1, 1, v229
	v_cmp_lt_i32_e32 vcc, v1, v4
	v_lshlrev_b32_e32 v4, 7, v6
	v_lshl_add_u64 v[124:125], s[24:25], 0, v[4:5]
	v_cndmask_b32_e32 v1, v229, v1, vcc
	v_lshlrev_b32_e32 v245, 2, v1
	v_lshl_add_u64 v[126:127], s[22:23], 0, v[4:5]
	v_lshl_add_u64 v[128:129], s[2:3], 0, v[4:5]
	s_mov_b64 s[22:23], 0
	v_lshlrev_b32_e32 v130, 2, v2
	v_lshlrev_b32_e32 v132, 2, v0
	s_branch .LBB0_328

.LBB0_328:
	v_ashrrev_i32_e32 v117, 31, v116
	v_lshlrev_b64 v[0:1], 11, v[116:117]
	v_lshl_add_u64 v[134:135], v[122:123], 0, v[0:1]
	global_load_dwordx4 v[12:15], v[134:135], off
	global_load_dwordx4 v[0:3], v[134:135], off offset:16
	v_readlane_b32 s2, v249, 30
	v_readlane_b32 s3, v249, 31
	s_load_dwordx2 s[2:3], s[2:3], 0x180
	v_lshlrev_b64 v[136:137], 10, v[116:117]
	v_mov_b32_e32 v131, v80
	v_mov_b32_e32 v133, v80
	s_movk_i32 s43, 0x80
	s_waitcnt lgkmcnt(0)
	v_lshl_add_u64 v[4:5], s[2:3], 0, v[136:137]
	v_lshl_add_u64 v[18:19], v[4:5], 0, v[130:131]
	v_lshl_add_u64 v[16:17], v[4:5], 0, v[132:133]
	global_load_dword v26, v[16:17], off offset:64
	global_load_dword v28, v[18:19], off
	global_load_dword v25, v[16:17], off offset:192
	global_load_dword v27, v[18:19], off offset:128
	global_load_dwordx4 v[4:7], v[134:135], off offset:48
	global_load_dwordx4 v[8:11], v[134:135], off offset:32
	global_load_dword v21, v[18:19], off offset:256
	global_load_dword v23, v[18:19], off offset:384
	global_load_dword v22, v[18:19], off offset:512
	global_load_dword v24, v[18:19], off offset:640
	global_load_dword v20, v[18:19], off offset:768
	s_nop 0
	global_load_dword v18, v[18:19], off offset:896
	s_nop 0
	global_load_dword v117, v[16:17], off offset:320
	global_load_dword v31, v[16:17], off offset:448
	global_load_dword v30, v[16:17], off offset:576
	global_load_dword v29, v[16:17], off offset:704
	global_load_dword v19, v[16:17], off offset:832
	s_nop 0
	global_load_dword v16, v[16:17], off offset:960
	s_movk_i32 s44, 0x3f80
	v_mov_b32_e32 v176, 0
	v_mov_b32_e32 v177, v176
	v_mov_b32_e32 v216, v176
	v_mov_b32_e32 v217, v176
	v_mov_b32_e32 v214, v176
	v_mov_b32_e32 v215, v176
	v_mov_b32_e32 v212, v176
	v_mov_b32_e32 v213, v176
	v_mov_b32_e32 v210, v176
	v_mov_b32_e32 v211, v176
	v_mov_b32_e32 v208, v176
	v_mov_b32_e32 v209, v176
	v_mov_b32_e32 v206, v176
	v_mov_b32_e32 v207, v176
	v_mov_b32_e32 v204, v176
	v_mov_b32_e32 v205, v176
	v_mov_b32_e32 v202, v176
	v_mov_b32_e32 v203, v176
	v_mov_b32_e32 v200, v176
	v_mov_b32_e32 v201, v176
	v_mov_b32_e32 v198, v176
	v_mov_b32_e32 v199, v176
	v_mov_b32_e32 v196, v176
	v_mov_b32_e32 v197, v176
	v_mov_b32_e32 v194, v176
	v_mov_b32_e32 v195, v176
	v_mov_b32_e32 v192, v176
	v_mov_b32_e32 v193, v176
	v_mov_b32_e32 v190, v176
	v_mov_b32_e32 v191, v176
	v_mov_b32_e32 v188, v176
	v_mov_b32_e32 v189, v176
	s_waitcnt vmcnt(17)
	v_cmp_lt_i32_e32 vcc, -1, v26
	s_waitcnt vmcnt(13)
	v_lshlrev_b32_e32 v160, 16, v4
	v_lshlrev_b32_e32 v152, 16, v12
	v_lshlrev_b32_e32 v174, 16, v1
	v_and_b32_e32 v143, 0xffff0000, v1
	v_cndmask_b32_e64 v1, v232, -1, vcc
	v_cmp_lt_i32_e32 vcc, -1, v28
	v_and_b32_e32 v150, 0xffff0000, v12
	v_lshlrev_b32_e32 v148, 16, v14
	v_cndmask_b32_e64 v12, v232, -1, vcc
	v_cmp_lt_i32_e32 vcc, -1, v25
	v_and_b32_e32 v146, 0xffff0000, v14
	v_lshlrev_b32_e32 v172, 16, v15
	v_cndmask_b32_e64 v17, v232, -1, vcc
	v_cmp_lt_i32_e32 vcc, -1, v27
	v_and_b32_e32 v147, 0xffff0000, v15
	v_lshlrev_b32_e32 v144, 16, v0
	v_and_b32_e32 v142, 0xffff0000, v0
	v_lshlrev_b32_e32 v140, 16, v2
	v_and_b32_e32 v138, 0xffff0000, v2
	v_and_b32_e32 v0, 0xffffff80, v26
	v_and_b32_e32 v2, 0xffffff80, v28
	v_and_b32_e32 v14, 0xffffff80, v25
	v_and_b32_e32 v15, 0xffffff80, v27
	v_cndmask_b32_e64 v32, v232, -1, vcc
	v_lshlrev_b32_e32 v170, 16, v13
	v_and_b32_e32 v151, 0xffff0000, v13
	v_xor_b32_e32 v1, v1, v0
	v_xor_b32_e32 v13, v12, v2
	v_xor_b32_e32 v0, v17, v14
	v_xor_b32_e32 v12, v32, v15
	v_pk_add_f32 v[0:1], v[12:13], v[0:1]
	v_lshlrev_b32_e32 v178, 16, v3
	v_or_b32_e32 v2, 0x80000000, v1
	v_not_b32_e32 v12, v1
	v_cmp_gt_i32_e32 vcc, 0, v1
	v_and_b32_e32 v139, 0xffff0000, v3
	s_waitcnt vmcnt(12)
	v_lshlrev_b32_e32 v168, 16, v8
	v_cndmask_b32_e32 v2, v2, v12, vcc
	v_and_b32_e32 v2, 0xffffffc0, v2
	v_cndmask_b32_e64 v2, 0, v2, s[10:11]
	v_bitop3_b32 v2, v2, 63, v81 bitop3:0x36
	v_and_b32_e32 v166, 0xffff0000, v8
	s_nop 1
	v_max_u32_dpp v250, v2, v2 quad_perm:[1,0,3,2] row_mask:0xf bank_mask:0xf
	v_min_u32_dpp v251, v2, v2 quad_perm:[1,0,3,2] row_mask:0xf bank_mask:0xf
	v_cndmask_b32_e64 v254, v251, v250, s[50:51]
	s_nop 1
	v_max_u32_dpp v250, v254, v254 quad_perm:[3,2,1,0] row_mask:0xf bank_mask:0xf
	v_min_u32_dpp v251, v254, v254 quad_perm:[3,2,1,0] row_mask:0xf bank_mask:0xf
	v_and_b32_e32 v158, 0xffff0000, v4
	v_lshlrev_b32_e32 v184, 16, v5
	v_cndmask_b32_e64 v2, v251, v250, s[52:53]
	s_nop 1
	v_and_b32_e32 v159, 0xffff0000, v5
	v_lshlrev_b32_e32 v156, 16, v6
	v_max_u32_dpp v250, v2, v2 quad_perm:[1,0,3,2] row_mask:0xf bank_mask:0xf
	v_min_u32_dpp v251, v2, v2 quad_perm:[1,0,3,2] row_mask:0xf bank_mask:0xf
	v_and_b32_e32 v154, 0xffff0000, v6
	v_cndmask_b32_e64 v254, v251, v250, s[50:51]
	s_nop 1
	v_lshlrev_b32_e32 v5, 7, v28
	v_and_b32_e32 v6, 0x7f, v26
	v_max_u32_dpp v2, v254, v254 row_half_mirror row_mask:0xf bank_mask:0x5
	v_min_u32_dpp v2, v254, v254 row_half_mirror row_mask:0xf bank_mask:0xa
	v_and_or_b32 v5, v5, s44, v6
	v_lshlrev_b32_e32 v186, 16, v7
	s_nop 1
	v_max_u32_dpp v250, v2, v2 quad_perm:[2,3,0,1] row_mask:0xf bank_mask:0xf
	v_and_b32_e32 v155, 0xffff0000, v7
	v_lshlrev_b32_e32 v164, 16, v10
	v_min_u32_dpp v251, v2, v2 quad_perm:[2,3,0,1] row_mask:0xf bank_mask:0xf
	v_cndmask_b32_e64 v254, v251, v250, s[52:53]
	v_and_b32_e32 v162, 0xffff0000, v10
	s_nop 1
	v_max_u32_dpp v250, v254, v254 quad_perm:[1,0,3,2] row_mask:0xf bank_mask:0xf
	v_lshlrev_b32_e32 v182, 16, v11
	v_min_u32_dpp v251, v254, v254 quad_perm:[1,0,3,2] row_mask:0xf bank_mask:0xf
	v_cndmask_b32_e64 v2, v251, v250, s[50:51]
	v_and_b32_e32 v163, 0xffff0000, v11
	s_nop 1
	v_max_u32_dpp v254, v2, v2 row_mirror row_mask:0xf bank_mask:0x3
	v_not_b32_e32 v17, v0
	v_min_u32_dpp v254, v2, v2 row_mirror row_mask:0xf bank_mask:0xc
	s_nop 1
	v_lshlrev_b32_e32 v180, 16, v9
	v_max_u32_dpp v2, v254, v254 row_ror:12 row_mask:0xf bank_mask:0x5
	v_min_u32_dpp v2, v254, v254 row_ror:4 row_mask:0xf bank_mask:0xa
	v_and_b32_e32 v167, 0xffff0000, v9
	s_nop 1
	v_max_u32_dpp v250, v2, v2 quad_perm:[2,3,0,1] row_mask:0xf bank_mask:0xf
	v_and_b32_e32 v9, 0x7f, v25
	v_min_u32_dpp v251, v2, v2 quad_perm:[2,3,0,1] row_mask:0xf bank_mask:0xf
	v_cndmask_b32_e64 v254, v251, v250, s[52:53]
	s_mov_b32 s24, 0
	s_nop 1
	v_max_u32_dpp v250, v254, v254 quad_perm:[1,0,3,2] row_mask:0xf bank_mask:0xf
	v_mov_b32_e32 v153, v150
	v_min_u32_dpp v251, v254, v254 quad_perm:[1,0,3,2] row_mask:0xf bank_mask:0xf
	v_cndmask_b32_e64 v2, v251, v250, s[50:51]
	v_mov_b32_e32 v171, v151
	ds_swizzle_b32 v252, v2 offset:0x7c1f
	s_waitcnt lgkmcnt(0)
	v_mov_b32_e32 v149, v146
	v_max_u32_dpp v254, v252, v2 quad_perm:[0,1,2,3] row_mask:0x5 bank_mask:0xf
	v_min_u32_dpp v254, v252, v2 quad_perm:[0,1,2,3] row_mask:0xa bank_mask:0xf
	v_mov_b32_e32 v173, v147
	s_nop 1
	v_max_u32_dpp v2, v254, v254 row_ror:8 row_mask:0xf bank_mask:0x3
	v_mov_b32_e32 v145, v142
	v_min_u32_dpp v2, v254, v254 row_ror:8 row_mask:0xf bank_mask:0xc
	s_nop 1
	v_mov_b32_e32 v175, v143
	v_max_u32_dpp v254, v2, v2 row_ror:12 row_mask:0xf bank_mask:0x5
	v_min_u32_dpp v254, v2, v2 row_ror:4 row_mask:0xf bank_mask:0xa
	v_mov_b32_e32 v141, v138
	s_nop 1
	v_max_u32_dpp v250, v254, v254 quad_perm:[2,3,0,1] row_mask:0xf bank_mask:0xf
	v_mov_b32_e32 v179, v139
	v_min_u32_dpp v251, v254, v254 quad_perm:[2,3,0,1] row_mask:0xf bank_mask:0xf
	v_cndmask_b32_e64 v2, v251, v250, s[52:53]
	v_mov_b32_e32 v169, v166
	s_nop 1
	v_max_u32_dpp v250, v2, v2 quad_perm:[1,0,3,2] row_mask:0xf bank_mask:0xf
	v_mov_b32_e32 v181, v167
	v_min_u32_dpp v251, v2, v2 quad_perm:[1,0,3,2] row_mask:0xf bank_mask:0xf
	v_cndmask_b32_e64 v254, v251, v250, s[50:51]
	v_mov_b32_e32 v165, v162
	v_xor_b32_e32 v253, 63, v81
	v_lshlrev_b32_e32 v253, 2, v253
	v_mov_b32_e32 v183, v163
	ds_bpermute_b32 v252, v253, v254
	s_waitcnt lgkmcnt(0)
	v_mov_b32_e32 v161, v158
	v_max_u32_dpp v2, v252, v254 quad_perm:[0,1,2,3] row_mask:0x3 bank_mask:0xf
	v_min_u32_dpp v2, v252, v254 quad_perm:[0,1,2,3] row_mask:0xc bank_mask:0xf
	v_mov_b32_e32 v185, v159
	ds_swizzle_b32 v252, v2 offset:0x401f
	s_waitcnt lgkmcnt(0)
	v_mov_b32_e32 v157, v154
	v_max_u32_dpp v254, v252, v2 quad_perm:[0,1,2,3] row_mask:0x5 bank_mask:0xf
	v_min_u32_dpp v254, v252, v2 quad_perm:[0,1,2,3] row_mask:0xa bank_mask:0xf
	v_mov_b32_e32 v187, v155
	s_nop 1
	v_max_u32_dpp v2, v254, v254 row_ror:8 row_mask:0xf bank_mask:0x3
	v_min_u32_dpp v2, v254, v254 row_ror:8 row_mask:0xf bank_mask:0xc
	s_nop 1
	v_max_u32_dpp v254, v2, v2 row_ror:12 row_mask:0xf bank_mask:0x5
	v_min_u32_dpp v254, v2, v2 row_ror:4 row_mask:0xf bank_mask:0xa
	s_nop 1
	v_max_u32_dpp v250, v254, v254 quad_perm:[2,3,0,1] row_mask:0xf bank_mask:0xf
	v_min_u32_dpp v251, v254, v254 quad_perm:[2,3,0,1] row_mask:0xf bank_mask:0xf
	v_cndmask_b32_e64 v2, v251, v250, s[52:53]
	s_nop 1
	v_max_u32_dpp v250, v2, v2 quad_perm:[1,0,3,2] row_mask:0xf bank_mask:0xf
	v_min_u32_dpp v251, v2, v2 quad_perm:[1,0,3,2] row_mask:0xf bank_mask:0xf
	v_cndmask_b32_e64 v254, v251, v250, s[50:51]
	v_not_b32_e32 v253, v254
	v_and_b32_e32 v253, 63, v253
	v_lshlrev_b32_e32 v253, 2, v253
	ds_permute_b32 v2, v253, v81
	s_waitcnt lgkmcnt(0)
	v_lshlrev_b32_e32 v13, 3, v2
	v_lshlrev_b32_e32 v12, 7, v2
	v_and_b32_e32 v13, 0x70, v13
	v_and_or_b32 v12, v12, s43, v13
	v_cmp_gt_u32_e32 vcc, 16, v2
	s_nop 1
	v_cndmask_b32_e32 v2, 4, v12, vcc
	ds_permute_b32 v1, v2, v1
	ds_permute_b32 v2, v2, v5
	s_waitcnt lgkmcnt(1)
	v_readlane_b32 s2, v1, 0
	s_nop 1
	v_subrev_f32_e32 v1, s2, v1
	v_mul_f32_e32 v1, 0x3fb8aa3b, v1
	v_exp_f32_e32 v1, v1
	s_waitcnt lgkmcnt(0)
	v_readlane_b32 s25, v2, 4
	v_readlane_b32 s26, v2, 36
	v_readlane_b32 s27, v2, 8
	v_cndmask_b32_e64 v1, 0, v1, s[12:13]
	ds_bpermute_b32 v3, v240, v1
	v_readlane_b32 s30, v2, 40
	v_readlane_b32 s31, v2, 12
	v_readlane_b32 s34, v2, 44
	v_readlane_b32 s35, v2, 16
	s_waitcnt lgkmcnt(0)
	v_add_f32_e32 v3, v1, v3
	ds_bpermute_b32 v8, v241, v3
	v_readlane_b32 s36, v2, 48
	v_readlane_b32 s37, v2, 20
	v_readlane_b32 s38, v2, 52
	v_readlane_b32 s39, v2, 24
	s_waitcnt lgkmcnt(0)
	v_add_f32_e32 v3, v3, v8
	ds_bpermute_b32 v4, v242, v3
	v_readlane_b32 s40, v2, 56
	v_readlane_b32 s41, v2, 28
	v_readlane_b32 s42, v2, 60
	v_lshlrev_b32_e32 v8, 7, v27
	s_waitcnt lgkmcnt(0)
	v_add_f32_e32 v3, v3, v4
	ds_bpermute_b32 v4, v243, v3
	v_and_or_b32 v8, v8, s44, v9
	s_waitcnt lgkmcnt(0)
	v_add_f32_e32 v3, v3, v4
	v_div_scale_f32 v4, s[2:3], v3, v3, v1
	v_rcp_f32_e32 v6, v4
	v_readlane_b32 s2, v2, 0
	v_readlane_b32 s3, v2, 32
	v_fma_f32 v5, -v4, v6, 1.0
	v_fmac_f32_e32 v6, v5, v6
	v_div_scale_f32 v5, vcc, v1, v3, v1
	v_mul_f32_e32 v7, v5, v6
	v_fma_f32 v10, -v4, v7, v5
	v_fmac_f32_e32 v7, v10, v6
	v_fma_f32 v4, -v4, v7, v5
	v_div_fmas_f32 v4, v4, v6, v7
	v_div_fixup_f32 v3, v4, v3, v1
	v_mov_b32_e32 v1, s2
	v_mov_b32_e32 v4, s3
	v_cndmask_b32_e64 v1, v1, v4, s[6:7]
	v_mad_i64_i32 v[4:5], s[2:3], v1, s28, v[118:119]
	global_load_dwordx2 v[36:37], v[4:5], off offset:16
	global_load_dwordx4 v[32:35], v[4:5], off
	v_mov_b32_e32 v4, s25
	v_mov_b32_e32 v5, s26
	v_cndmask_b32_e64 v6, v4, v5, s[6:7]
	v_mad_i64_i32 v[4:5], s[2:3], v6, s28, v[118:119]
	global_load_dwordx2 v[42:43], v[4:5], off offset:16
	global_load_dwordx4 v[38:41], v[4:5], off
	v_mov_b32_e32 v4, s27
	v_mov_b32_e32 v5, s30
	v_cndmask_b32_e64 v10, v4, v5, s[6:7]
	v_mad_i64_i32 v[4:5], s[2:3], v10, s28, v[118:119]
	global_load_dwordx2 v[48:49], v[4:5], off offset:16
	global_load_dwordx4 v[44:47], v[4:5], off
	v_mov_b32_e32 v4, s31
	v_mov_b32_e32 v5, s34
	v_cndmask_b32_e64 v11, v4, v5, s[6:7]
	v_mad_i64_i32 v[4:5], s[2:3], v11, s28, v[118:119]
	global_load_dwordx2 v[54:55], v[4:5], off offset:16
	global_load_dwordx4 v[50:53], v[4:5], off
	v_mov_b32_e32 v4, s35
	v_mov_b32_e32 v5, s36
	v_cndmask_b32_e64 v12, v4, v5, s[6:7]
	v_mad_i64_i32 v[4:5], s[2:3], v12, s28, v[118:119]
	global_load_dwordx2 v[60:61], v[4:5], off offset:16
	global_load_dwordx4 v[56:59], v[4:5], off
	v_mov_b32_e32 v4, s37
	v_mov_b32_e32 v5, s38
	v_cndmask_b32_e64 v13, v4, v5, s[6:7]
	v_mad_i64_i32 v[4:5], s[2:3], v13, s28, v[118:119]
	global_load_dwordx2 v[66:67], v[4:5], off offset:16
	global_load_dwordx4 v[62:65], v[4:5], off
	v_mov_b32_e32 v4, s39
	v_mov_b32_e32 v5, s40
	v_cndmask_b32_e64 v14, v4, v5, s[6:7]
	v_mad_i64_i32 v[4:5], s[2:3], v14, s28, v[118:119]
	global_load_dwordx2 v[72:73], v[4:5], off offset:16
	global_load_dwordx4 v[68:71], v[4:5], off
	v_mov_b32_e32 v4, s41
	v_mov_b32_e32 v5, s42
	v_cndmask_b32_e64 v15, v4, v5, s[6:7]
	v_mad_i64_i32 v[4:5], s[2:3], v15, s28, v[118:119]
	global_load_dwordx2 v[78:79], v[4:5], off offset:16
	global_load_dwordx4 v[74:77], v[4:5], off
	v_mad_i64_i32 v[4:5], s[2:3], v1, s28, v[120:121]
	v_or_b32_e32 v1, 0x80000000, v0
	v_cmp_gt_i32_e32 vcc, 0, v0
	v_mad_i64_i32 v[6:7], s[2:3], v6, s28, v[120:121]
	s_nop 0
	v_cndmask_b32_e32 v1, v1, v17, vcc
	v_and_b32_e32 v1, 0xffffffc0, v1
	v_cndmask_b32_e64 v1, 0, v1, s[10:11]
	v_bitop3_b32 v1, v1, 63, v81 bitop3:0x36
	global_load_dwordx4 v[110:113], v[4:5], off offset:768
	global_load_dwordx4 v[106:109], v[6:7], off offset:768
	s_nop 1
	v_max_u32_dpp v250, v1, v1 quad_perm:[1,0,3,2] row_mask:0xf bank_mask:0xf
	v_min_u32_dpp v251, v1, v1 quad_perm:[1,0,3,2] row_mask:0xf bank_mask:0xf
	v_cndmask_b32_e64 v17, v251, v250, s[50:51]
	s_nop 1
	v_max_u32_dpp v250, v17, v17 quad_perm:[3,2,1,0] row_mask:0xf bank_mask:0xf
	v_min_u32_dpp v251, v17, v17 quad_perm:[3,2,1,0] row_mask:0xf bank_mask:0xf
	v_cndmask_b32_e64 v1, v251, v250, s[52:53]
	s_nop 1
	v_max_u32_dpp v250, v1, v1 quad_perm:[1,0,3,2] row_mask:0xf bank_mask:0xf
	v_min_u32_dpp v251, v1, v1 quad_perm:[1,0,3,2] row_mask:0xf bank_mask:0xf
	v_cndmask_b32_e64 v17, v251, v250, s[50:51]
	s_nop 1
	v_max_u32_dpp v1, v17, v17 row_half_mirror row_mask:0xf bank_mask:0x5
	v_min_u32_dpp v1, v17, v17 row_half_mirror row_mask:0xf bank_mask:0xa
	s_nop 1
	v_max_u32_dpp v250, v1, v1 quad_perm:[2,3,0,1] row_mask:0xf bank_mask:0xf
	v_min_u32_dpp v251, v1, v1 quad_perm:[2,3,0,1] row_mask:0xf bank_mask:0xf
	v_cndmask_b32_e64 v17, v251, v250, s[52:53]
	s_nop 1
	v_max_u32_dpp v250, v17, v17 quad_perm:[1,0,3,2] row_mask:0xf bank_mask:0xf
	v_min_u32_dpp v251, v17, v17 quad_perm:[1,0,3,2] row_mask:0xf bank_mask:0xf
	v_cndmask_b32_e64 v1, v251, v250, s[50:51]
	s_nop 1
	v_max_u32_dpp v17, v1, v1 row_mirror row_mask:0xf bank_mask:0x3
	v_min_u32_dpp v17, v1, v1 row_mirror row_mask:0xf bank_mask:0xc
	s_nop 1
	v_max_u32_dpp v1, v17, v17 row_ror:12 row_mask:0xf bank_mask:0x5
	v_min_u32_dpp v1, v17, v17 row_ror:4 row_mask:0xf bank_mask:0xa
	s_nop 1
	v_max_u32_dpp v250, v1, v1 quad_perm:[2,3,0,1] row_mask:0xf bank_mask:0xf
	v_min_u32_dpp v251, v1, v1 quad_perm:[2,3,0,1] row_mask:0xf bank_mask:0xf
	v_cndmask_b32_e64 v17, v251, v250, s[52:53]
	s_nop 1
	v_max_u32_dpp v250, v17, v17 quad_perm:[1,0,3,2] row_mask:0xf bank_mask:0xf
	v_min_u32_dpp v251, v17, v17 quad_perm:[1,0,3,2] row_mask:0xf bank_mask:0xf
	v_cndmask_b32_e64 v1, v251, v250, s[50:51]
	ds_swizzle_b32 v252, v1 offset:0x7c1f
	s_waitcnt lgkmcnt(0)
	v_max_u32_dpp v17, v252, v1 quad_perm:[0,1,2,3] row_mask:0x5 bank_mask:0xf
	v_min_u32_dpp v17, v252, v1 quad_perm:[0,1,2,3] row_mask:0xa bank_mask:0xf
	s_nop 1
	v_max_u32_dpp v1, v17, v17 row_ror:8 row_mask:0xf bank_mask:0x3
	v_min_u32_dpp v1, v17, v17 row_ror:8 row_mask:0xf bank_mask:0xc
	s_nop 1
	v_max_u32_dpp v17, v1, v1 row_ror:12 row_mask:0xf bank_mask:0x5
	v_min_u32_dpp v17, v1, v1 row_ror:4 row_mask:0xf bank_mask:0xa
	s_nop 1
	v_max_u32_dpp v250, v17, v17 quad_perm:[2,3,0,1] row_mask:0xf bank_mask:0xf
	v_min_u32_dpp v251, v17, v17 quad_perm:[2,3,0,1] row_mask:0xf bank_mask:0xf
	v_cndmask_b32_e64 v1, v251, v250, s[52:53]
	s_nop 1
	v_max_u32_dpp v250, v1, v1 quad_perm:[1,0,3,2] row_mask:0xf bank_mask:0xf
	v_min_u32_dpp v251, v1, v1 quad_perm:[1,0,3,2] row_mask:0xf bank_mask:0xf
	v_cndmask_b32_e64 v17, v251, v250, s[50:51]
	v_xor_b32_e32 v253, 63, v81
	v_lshlrev_b32_e32 v253, 2, v253
	ds_bpermute_b32 v252, v253, v17
	s_waitcnt lgkmcnt(0)
	v_max_u32_dpp v1, v252, v17 quad_perm:[0,1,2,3] row_mask:0x3 bank_mask:0xf
	v_min_u32_dpp v1, v252, v17 quad_perm:[0,1,2,3] row_mask:0xc bank_mask:0xf
	ds_swizzle_b32 v252, v1 offset:0x401f
	s_waitcnt lgkmcnt(0)
	v_max_u32_dpp v17, v252, v1 quad_perm:[0,1,2,3] row_mask:0x5 bank_mask:0xf
	v_min_u32_dpp v17, v252, v1 quad_perm:[0,1,2,3] row_mask:0xa bank_mask:0xf
	s_nop 1
	v_max_u32_dpp v1, v17, v17 row_ror:8 row_mask:0xf bank_mask:0x3
	v_min_u32_dpp v1, v17, v17 row_ror:8 row_mask:0xf bank_mask:0xc
	s_nop 1
	v_max_u32_dpp v17, v1, v1 row_ror:12 row_mask:0xf bank_mask:0x5
	v_min_u32_dpp v17, v1, v1 row_ror:4 row_mask:0xf bank_mask:0xa
	s_nop 1
	v_max_u32_dpp v250, v17, v17 quad_perm:[2,3,0,1] row_mask:0xf bank_mask:0xf
	v_min_u32_dpp v251, v17, v17 quad_perm:[2,3,0,1] row_mask:0xf bank_mask:0xf
	v_cndmask_b32_e64 v1, v251, v250, s[52:53]
	s_nop 1
	v_max_u32_dpp v250, v1, v1 quad_perm:[1,0,3,2] row_mask:0xf bank_mask:0xf
	v_min_u32_dpp v251, v1, v1 quad_perm:[1,0,3,2] row_mask:0xf bank_mask:0xf
	v_cndmask_b32_e64 v17, v251, v250, s[50:51]
	v_not_b32_e32 v253, v17
	v_and_b32_e32 v253, 63, v253
	v_lshlrev_b32_e32 v253, 2, v253
	ds_permute_b32 v1, v253, v81
	s_waitcnt lgkmcnt(0)
	v_lshlrev_b32_e32 v25, 3, v1
	v_lshlrev_b32_e32 v17, 7, v1
	v_and_b32_e32 v25, 0x70, v25
	v_and_or_b32 v17, v17, s43, v25
	v_cmp_gt_u32_e32 vcc, 16, v1
	s_nop 1
	v_cndmask_b32_e32 v17, 4, v17, vcc
	ds_permute_b32 v25, v17, v0
	v_mad_i64_i32 v[0:1], s[2:3], v10, s28, v[120:121]
	s_waitcnt vmcnt(23)
	v_cmp_lt_i32_e32 vcc, -1, v117
	s_waitcnt lgkmcnt(0)
	v_readlane_b32 s2, v25, 0
	s_nop 1
	v_subrev_f32_e32 v4, s2, v25
	v_mul_f32_e32 v4, 0x3fb8aa3b, v4
	v_exp_f32_e32 v6, v4
	v_mad_i64_i32 v[4:5], s[2:3], v11, s28, v[120:121]
	global_load_dwordx4 v[102:105], v[0:1], off offset:768
	global_load_dwordx4 v[98:101], v[4:5], off offset:768
	v_cndmask_b32_e64 v6, 0, v6, s[12:13]
	ds_bpermute_b32 v7, v240, v6
	v_mad_i64_i32 v[0:1], s[2:3], v12, s28, v[120:121]
	v_mad_i64_i32 v[4:5], s[2:3], v13, s28, v[120:121]
	s_waitcnt lgkmcnt(0)
	v_add_f32_e32 v7, v6, v7
	ds_bpermute_b32 v10, v241, v7
	global_load_dwordx4 v[94:97], v[0:1], off offset:768
	global_load_dwordx4 v[90:93], v[4:5], off offset:768
	v_mad_i64_i32 v[0:1], s[2:3], v14, s28, v[120:121]
	v_mad_i64_i32 v[4:5], s[2:3], v15, s28, v[120:121]
	s_waitcnt lgkmcnt(0)
	v_add_f32_e32 v7, v7, v10
	ds_bpermute_b32 v10, v242, v7
	global_load_dwordx4 v[86:89], v[0:1], off offset:768
	global_load_dwordx4 v[82:85], v[4:5], off offset:768
	v_cndmask_b32_e64 v1, v232, -1, vcc
	v_cmp_lt_i32_e32 vcc, -1, v21
	v_and_b32_e32 v0, 0xffffff80, v117
	s_waitcnt lgkmcnt(0)
	v_add_f32_e32 v7, v7, v10
	v_cndmask_b32_e64 v5, v232, -1, vcc
	s_waitcnt vmcnt(28)
	v_cmp_lt_i32_e32 vcc, -1, v31
	v_and_b32_e32 v4, 0xffffff80, v21
	v_xor_b32_e32 v1, v1, v0
	v_cndmask_b32_e64 v10, v232, -1, vcc
	v_cmp_lt_i32_e32 vcc, -1, v23
	v_xor_b32_e32 v5, v5, v4
	v_and_b32_e32 v0, 0xffffff80, v31
	v_and_b32_e32 v4, 0xffffff80, v23
	v_cndmask_b32_e64 v11, v232, -1, vcc
	v_xor_b32_e32 v0, v10, v0
	v_xor_b32_e32 v4, v11, v4
	v_pk_add_f32 v[0:1], v[4:5], v[0:1]
	ds_bpermute_b32 v9, v243, v7
	v_or_b32_e32 v4, 0x80000000, v1
	v_not_b32_e32 v5, v1
	v_cmp_gt_i32_e32 vcc, 0, v1
	s_nop 1
	v_cndmask_b32_e32 v4, v4, v5, vcc
	v_and_b32_e32 v4, 0xffffffc0, v4
	v_cndmask_b32_e64 v4, 0, v4, s[10:11]
	v_bitop3_b32 v4, v4, 63, v81 bitop3:0x36
	s_nop 0
	s_nop 1
	v_max_u32_dpp v250, v4, v4 quad_perm:[1,0,3,2] row_mask:0xf bank_mask:0xf
	v_min_u32_dpp v251, v4, v4 quad_perm:[1,0,3,2] row_mask:0xf bank_mask:0xf
	v_cndmask_b32_e64 v5, v251, v250, s[50:51]
	s_nop 1
	v_max_u32_dpp v250, v5, v5 quad_perm:[3,2,1,0] row_mask:0xf bank_mask:0xf
	v_min_u32_dpp v251, v5, v5 quad_perm:[3,2,1,0] row_mask:0xf bank_mask:0xf
	v_cndmask_b32_e64 v4, v251, v250, s[52:53]
	s_nop 1
	v_max_u32_dpp v250, v4, v4 quad_perm:[1,0,3,2] row_mask:0xf bank_mask:0xf
	v_min_u32_dpp v251, v4, v4 quad_perm:[1,0,3,2] row_mask:0xf bank_mask:0xf
	v_cndmask_b32_e64 v5, v251, v250, s[50:51]
	s_nop 1
	v_max_u32_dpp v4, v5, v5 row_half_mirror row_mask:0xf bank_mask:0x5
	v_min_u32_dpp v4, v5, v5 row_half_mirror row_mask:0xf bank_mask:0xa
	s_nop 1
	v_max_u32_dpp v250, v4, v4 quad_perm:[2,3,0,1] row_mask:0xf bank_mask:0xf
	v_min_u32_dpp v251, v4, v4 quad_perm:[2,3,0,1] row_mask:0xf bank_mask:0xf
	v_cndmask_b32_e64 v5, v251, v250, s[52:53]
	s_nop 1
	v_max_u32_dpp v250, v5, v5 quad_perm:[1,0,3,2] row_mask:0xf bank_mask:0xf
	v_min_u32_dpp v251, v5, v5 quad_perm:[1,0,3,2] row_mask:0xf bank_mask:0xf
	v_cndmask_b32_e64 v4, v251, v250, s[50:51]
	s_nop 1
	v_max_u32_dpp v5, v4, v4 row_mirror row_mask:0xf bank_mask:0x3
	v_min_u32_dpp v5, v4, v4 row_mirror row_mask:0xf bank_mask:0xc
	s_nop 1
	v_max_u32_dpp v4, v5, v5 row_ror:12 row_mask:0xf bank_mask:0x5
	v_min_u32_dpp v4, v5, v5 row_ror:4 row_mask:0xf bank_mask:0xa
	s_nop 1
	v_max_u32_dpp v250, v4, v4 quad_perm:[2,3,0,1] row_mask:0xf bank_mask:0xf
	v_min_u32_dpp v251, v4, v4 quad_perm:[2,3,0,1] row_mask:0xf bank_mask:0xf
	v_cndmask_b32_e64 v5, v251, v250, s[52:53]
	s_nop 1
	v_max_u32_dpp v250, v5, v5 quad_perm:[1,0,3,2] row_mask:0xf bank_mask:0xf
	v_min_u32_dpp v251, v5, v5 quad_perm:[1,0,3,2] row_mask:0xf bank_mask:0xf
	v_cndmask_b32_e64 v4, v251, v250, s[50:51]
	ds_swizzle_b32 v252, v4 offset:0x7c1f
	s_waitcnt lgkmcnt(0)
	v_max_u32_dpp v5, v252, v4 quad_perm:[0,1,2,3] row_mask:0x5 bank_mask:0xf
	v_min_u32_dpp v5, v252, v4 quad_perm:[0,1,2,3] row_mask:0xa bank_mask:0xf
	s_nop 1
	v_max_u32_dpp v4, v5, v5 row_ror:8 row_mask:0xf bank_mask:0x3
	v_min_u32_dpp v4, v5, v5 row_ror:8 row_mask:0xf bank_mask:0xc
	s_nop 1
	v_max_u32_dpp v5, v4, v4 row_ror:12 row_mask:0xf bank_mask:0x5
	v_min_u32_dpp v5, v4, v4 row_ror:4 row_mask:0xf bank_mask:0xa
	s_nop 1
	v_max_u32_dpp v250, v5, v5 quad_perm:[2,3,0,1] row_mask:0xf bank_mask:0xf
	v_min_u32_dpp v251, v5, v5 quad_perm:[2,3,0,1] row_mask:0xf bank_mask:0xf
	v_cndmask_b32_e64 v4, v251, v250, s[52:53]
	s_nop 1
	v_max_u32_dpp v250, v4, v4 quad_perm:[1,0,3,2] row_mask:0xf bank_mask:0xf
	v_min_u32_dpp v251, v4, v4 quad_perm:[1,0,3,2] row_mask:0xf bank_mask:0xf
	v_cndmask_b32_e64 v5, v251, v250, s[50:51]
	v_xor_b32_e32 v253, 63, v81
	v_lshlrev_b32_e32 v253, 2, v253
	ds_bpermute_b32 v252, v253, v5
	s_waitcnt lgkmcnt(0)
	v_max_u32_dpp v4, v252, v5 quad_perm:[0,1,2,3] row_mask:0x3 bank_mask:0xf
	v_min_u32_dpp v4, v252, v5 quad_perm:[0,1,2,3] row_mask:0xc bank_mask:0xf
	ds_swizzle_b32 v252, v4 offset:0x401f
	s_waitcnt lgkmcnt(0)
	v_max_u32_dpp v5, v252, v4 quad_perm:[0,1,2,3] row_mask:0x5 bank_mask:0xf
	v_min_u32_dpp v5, v252, v4 quad_perm:[0,1,2,3] row_mask:0xa bank_mask:0xf
	s_nop 1
	v_max_u32_dpp v4, v5, v5 row_ror:8 row_mask:0xf bank_mask:0x3
	v_min_u32_dpp v4, v5, v5 row_ror:8 row_mask:0xf bank_mask:0xc
	s_nop 1
	v_max_u32_dpp v5, v4, v4 row_ror:12 row_mask:0xf bank_mask:0x5
	v_min_u32_dpp v5, v4, v4 row_ror:4 row_mask:0xf bank_mask:0xa
	s_nop 1
	v_max_u32_dpp v250, v5, v5 quad_perm:[2,3,0,1] row_mask:0xf bank_mask:0xf
	v_min_u32_dpp v251, v5, v5 quad_perm:[2,3,0,1] row_mask:0xf bank_mask:0xf
	v_cndmask_b32_e64 v4, v251, v250, s[52:53]
	s_nop 1
	v_max_u32_dpp v250, v4, v4 quad_perm:[1,0,3,2] row_mask:0xf bank_mask:0xf
	v_min_u32_dpp v251, v4, v4 quad_perm:[1,0,3,2] row_mask:0xf bank_mask:0xf
	v_cndmask_b32_e64 v5, v251, v250, s[50:51]
	v_not_b32_e32 v253, v5
	v_and_b32_e32 v253, 63, v253
	v_lshlrev_b32_e32 v253, 2, v253
	ds_permute_b32 v4, v253, v81
	s_waitcnt lgkmcnt(0)
	v_lshlrev_b32_e32 v10, 3, v4
	v_lshlrev_b32_e32 v5, 7, v4
	v_and_b32_e32 v10, 0x70, v10
	v_and_or_b32 v5, v5, s43, v10
	v_cmp_gt_u32_e32 vcc, 16, v4
	ds_permute_b32 v4, v17, v8
	s_nop 0
	v_cndmask_b32_e32 v10, 4, v5, vcc
	ds_permute_b32 v1, v10, v1
	s_waitcnt lgkmcnt(2)
	v_add_f32_e32 v5, v7, v9
	v_div_scale_f32 v7, s[2:3], v5, v5, v6
	v_rcp_f32_e32 v9, v7
	s_waitcnt lgkmcnt(0)
	v_readlane_b32 s2, v1, 0
	v_div_scale_f32 v11, vcc, v6, v5, v6
	s_nop 0
	v_subrev_f32_e32 v1, s2, v1
	v_mul_f32_e32 v1, 0x3fb8aa3b, v1
	v_exp_f32_e32 v1, v1
	v_fma_f32 v8, -v7, v9, 1.0
	v_fmac_f32_e32 v9, v8, v9
	v_mul_f32_e32 v12, v11, v9
	v_cndmask_b32_e64 v1, 0, v1, s[12:13]
	ds_bpermute_b32 v8, v240, v1
	v_fma_f32 v13, -v7, v12, v11
	v_fmac_f32_e32 v12, v13, v9
	v_fma_f32 v7, -v7, v12, v11
	v_div_fmas_f32 v7, v7, v9, v12
	s_waitcnt lgkmcnt(0)
	v_add_f32_e32 v8, v1, v8
	ds_bpermute_b32 v14, v241, v8
	v_div_fixup_f32 v5, v7, v5, v6
	v_or_b32_e32 v6, 0x80000000, v0
	v_not_b32_e32 v7, v0
	v_cmp_gt_i32_e32 vcc, 0, v0
	s_waitcnt lgkmcnt(0)
	v_add_f32_e32 v8, v8, v14
	ds_bpermute_b32 v9, v242, v8
	v_cndmask_b32_e32 v6, v6, v7, vcc
	v_and_b32_e32 v6, 0xffffffc0, v6
	v_cndmask_b32_e64 v6, 0, v6, s[10:11]
	v_bitop3_b32 v6, v6, 63, v81 bitop3:0x36
	ds_write2st64_b64 v239, v[2:3], v[4:5] offset1:1
	s_nop 1
	s_waitcnt lgkmcnt(1)
	v_add_f32_e32 v4, v8, v9
	v_max_u32_dpp v250, v6, v6 quad_perm:[1,0,3,2] row_mask:0xf bank_mask:0xf
	ds_bpermute_b32 v5, v243, v4
	v_min_u32_dpp v251, v6, v6 quad_perm:[1,0,3,2] row_mask:0xf bank_mask:0xf
	v_cndmask_b32_e64 v7, v251, v250, s[50:51]
	v_lshlrev_b32_e32 v2, 7, v21
	s_nop 1
	v_max_u32_dpp v250, v7, v7 quad_perm:[3,2,1,0] row_mask:0xf bank_mask:0xf
	v_min_u32_dpp v251, v7, v7 quad_perm:[3,2,1,0] row_mask:0xf bank_mask:0xf
	v_and_b32_e32 v3, 0x7f, v117
	v_cndmask_b32_e64 v6, v251, v250, s[52:53]
	s_nop 1
	v_max_u32_dpp v250, v6, v6 quad_perm:[1,0,3,2] row_mask:0xf bank_mask:0xf
	v_and_or_b32 v2, v2, s44, v3
	v_min_u32_dpp v251, v6, v6 quad_perm:[1,0,3,2] row_mask:0xf bank_mask:0xf
	v_cndmask_b32_e64 v7, v251, v250, s[50:51]
	s_nop 1
	s_waitcnt lgkmcnt(0)
	v_max_u32_dpp v6, v7, v7 row_half_mirror row_mask:0xf bank_mask:0x5
	v_add_f32_e32 v3, v4, v5
	v_min_u32_dpp v6, v7, v7 row_half_mirror row_mask:0xf bank_mask:0xa
	s_nop 1
	v_max_u32_dpp v250, v6, v6 quad_perm:[2,3,0,1] row_mask:0xf bank_mask:0xf
	ds_permute_b32 v2, v10, v2
	v_min_u32_dpp v251, v6, v6 quad_perm:[2,3,0,1] row_mask:0xf bank_mask:0xf
	v_cndmask_b32_e64 v7, v251, v250, s[52:53]
	s_nop 1
	v_max_u32_dpp v250, v7, v7 quad_perm:[1,0,3,2] row_mask:0xf bank_mask:0xf
	v_min_u32_dpp v251, v7, v7 quad_perm:[1,0,3,2] row_mask:0xf bank_mask:0xf
	v_cndmask_b32_e64 v6, v251, v250, s[50:51]
	s_nop 1
	v_max_u32_dpp v7, v6, v6 row_mirror row_mask:0xf bank_mask:0x3
	v_min_u32_dpp v7, v6, v6 row_mirror row_mask:0xf bank_mask:0xc
	s_nop 1
	v_max_u32_dpp v6, v7, v7 row_ror:12 row_mask:0xf bank_mask:0x5
	v_min_u32_dpp v6, v7, v7 row_ror:4 row_mask:0xf bank_mask:0xa
	s_nop 1
	v_max_u32_dpp v250, v6, v6 quad_perm:[2,3,0,1] row_mask:0xf bank_mask:0xf
	v_min_u32_dpp v251, v6, v6 quad_perm:[2,3,0,1] row_mask:0xf bank_mask:0xf
	v_cndmask_b32_e64 v7, v251, v250, s[52:53]
	s_nop 1
	v_max_u32_dpp v250, v7, v7 quad_perm:[1,0,3,2] row_mask:0xf bank_mask:0xf
	v_min_u32_dpp v251, v7, v7 quad_perm:[1,0,3,2] row_mask:0xf bank_mask:0xf
	v_cndmask_b32_e64 v6, v251, v250, s[50:51]
	ds_swizzle_b32 v252, v6 offset:0x7c1f
	s_waitcnt lgkmcnt(0)
	v_max_u32_dpp v7, v252, v6 quad_perm:[0,1,2,3] row_mask:0x5 bank_mask:0xf
	v_min_u32_dpp v7, v252, v6 quad_perm:[0,1,2,3] row_mask:0xa bank_mask:0xf
	s_nop 1
	v_max_u32_dpp v6, v7, v7 row_ror:8 row_mask:0xf bank_mask:0x3
	v_min_u32_dpp v6, v7, v7 row_ror:8 row_mask:0xf bank_mask:0xc
	s_nop 1
	v_max_u32_dpp v7, v6, v6 row_ror:12 row_mask:0xf bank_mask:0x5
	v_min_u32_dpp v7, v6, v6 row_ror:4 row_mask:0xf bank_mask:0xa
	s_nop 1
	v_max_u32_dpp v250, v7, v7 quad_perm:[2,3,0,1] row_mask:0xf bank_mask:0xf
	v_min_u32_dpp v251, v7, v7 quad_perm:[2,3,0,1] row_mask:0xf bank_mask:0xf
	v_cndmask_b32_e64 v6, v251, v250, s[52:53]
	s_nop 1
	v_max_u32_dpp v250, v6, v6 quad_perm:[1,0,3,2] row_mask:0xf bank_mask:0xf
	v_min_u32_dpp v251, v6, v6 quad_perm:[1,0,3,2] row_mask:0xf bank_mask:0xf
	v_cndmask_b32_e64 v7, v251, v250, s[50:51]
	v_xor_b32_e32 v253, 63, v81
	v_lshlrev_b32_e32 v253, 2, v253
	ds_bpermute_b32 v252, v253, v7
	s_waitcnt lgkmcnt(0)
	v_max_u32_dpp v6, v252, v7 quad_perm:[0,1,2,3] row_mask:0x3 bank_mask:0xf
	v_min_u32_dpp v6, v252, v7 quad_perm:[0,1,2,3] row_mask:0xc bank_mask:0xf
	ds_swizzle_b32 v252, v6 offset:0x401f
	s_waitcnt lgkmcnt(0)
	v_max_u32_dpp v7, v252, v6 quad_perm:[0,1,2,3] row_mask:0x5 bank_mask:0xf
	v_min_u32_dpp v7, v252, v6 quad_perm:[0,1,2,3] row_mask:0xa bank_mask:0xf
	s_nop 1
	v_max_u32_dpp v6, v7, v7 row_ror:8 row_mask:0xf bank_mask:0x3
	v_min_u32_dpp v6, v7, v7 row_ror:8 row_mask:0xf bank_mask:0xc
	s_nop 1
	v_max_u32_dpp v7, v6, v6 row_ror:12 row_mask:0xf bank_mask:0x5
	v_min_u32_dpp v7, v6, v6 row_ror:4 row_mask:0xf bank_mask:0xa
	s_nop 1
	v_max_u32_dpp v250, v7, v7 quad_perm:[2,3,0,1] row_mask:0xf bank_mask:0xf
	v_min_u32_dpp v251, v7, v7 quad_perm:[2,3,0,1] row_mask:0xf bank_mask:0xf
	v_cndmask_b32_e64 v6, v251, v250, s[52:53]
	s_nop 1
	v_max_u32_dpp v250, v6, v6 quad_perm:[1,0,3,2] row_mask:0xf bank_mask:0xf
	v_min_u32_dpp v251, v6, v6 quad_perm:[1,0,3,2] row_mask:0xf bank_mask:0xf
	v_cndmask_b32_e64 v7, v251, v250, s[50:51]
	v_not_b32_e32 v253, v7
	v_and_b32_e32 v253, 63, v253
	v_lshlrev_b32_e32 v253, 2, v253
	ds_permute_b32 v6, v253, v81
	s_waitcnt lgkmcnt(0)
	v_lshlrev_b32_e32 v8, 3, v6
	v_lshlrev_b32_e32 v7, 7, v6
	v_and_b32_e32 v8, 0x70, v8
	v_and_or_b32 v7, v7, s43, v8
	v_cmp_gt_u32_e32 vcc, 16, v6
	v_and_b32_e32 v8, 0x7f, v31
	s_nop 0
	v_cndmask_b32_e32 v6, 4, v7, vcc
	ds_permute_b32 v0, v6, v0
	v_lshlrev_b32_e32 v7, 7, v23
	v_and_or_b32 v7, v7, s44, v8
	s_waitcnt lgkmcnt(0)
	v_readlane_b32 s2, v0, 0
	s_nop 1
	v_subrev_f32_e32 v0, s2, v0
	v_mul_f32_e32 v0, 0x3fb8aa3b, v0
	v_exp_f32_e32 v0, v0
	v_div_scale_f32 v4, s[2:3], v3, v3, v1
	v_rcp_f32_e32 v5, v4
	v_cndmask_b32_e64 v9, 0, v0, s[12:13]
	ds_bpermute_b32 v0, v240, v9
	v_fma_f32 v10, -v4, v5, 1.0
	v_fmac_f32_e32 v5, v10, v5
	v_div_scale_f32 v10, vcc, v1, v3, v1
	s_waitcnt lgkmcnt(0)
	v_add_f32_e32 v0, v9, v0
	ds_bpermute_b32 v11, v241, v0
	v_mul_f32_e32 v12, v10, v5
	v_fma_f32 v13, -v4, v12, v10
	v_fmac_f32_e32 v12, v13, v5
	v_fma_f32 v4, -v4, v12, v10
	s_waitcnt lgkmcnt(0)
	v_add_f32_e32 v0, v0, v11
	ds_bpermute_b32 v10, v242, v0
	v_div_fmas_f32 v4, v4, v5, v12
	s_waitcnt vmcnt(27)
	v_cmp_lt_i32_e32 vcc, -1, v30
	v_div_fixup_f32 v3, v4, v3, v1
	v_and_b32_e32 v4, 0xffffff80, v22
	v_cndmask_b32_e64 v1, v232, -1, vcc
	v_cmp_lt_i32_e32 vcc, -1, v22
	s_waitcnt lgkmcnt(0)
	v_add_f32_e32 v8, v0, v10
	v_and_b32_e32 v0, 0xffffff80, v30
	v_cndmask_b32_e64 v5, v232, -1, vcc
	s_waitcnt vmcnt(26)
	v_cmp_lt_i32_e32 vcc, -1, v29
	v_xor_b32_e32 v1, v1, v0
	v_xor_b32_e32 v5, v5, v4
	v_cndmask_b32_e64 v11, v232, -1, vcc
	v_cmp_lt_i32_e32 vcc, -1, v24
	v_and_b32_e32 v0, 0xffffff80, v29
	v_and_b32_e32 v4, 0xffffff80, v24
	v_cndmask_b32_e64 v12, v232, -1, vcc
	v_xor_b32_e32 v0, v11, v0
	v_xor_b32_e32 v4, v12, v4
	v_pk_add_f32 v[0:1], v[4:5], v[0:1]
	ds_bpermute_b32 v10, v243, v8
	v_or_b32_e32 v4, 0x80000000, v1
	v_not_b32_e32 v5, v1
	v_cmp_gt_i32_e32 vcc, 0, v1
	s_nop 1
	v_cndmask_b32_e32 v4, v4, v5, vcc
	v_and_b32_e32 v4, 0xffffffc0, v4
	v_cndmask_b32_e64 v4, 0, v4, s[10:11]
	v_bitop3_b32 v4, v4, 63, v81 bitop3:0x36
	s_nop 0
	s_nop 1
	v_max_u32_dpp v250, v4, v4 quad_perm:[1,0,3,2] row_mask:0xf bank_mask:0xf
	v_min_u32_dpp v251, v4, v4 quad_perm:[1,0,3,2] row_mask:0xf bank_mask:0xf
	v_cndmask_b32_e64 v5, v251, v250, s[50:51]
	s_nop 1
	v_max_u32_dpp v250, v5, v5 quad_perm:[3,2,1,0] row_mask:0xf bank_mask:0xf
	v_min_u32_dpp v251, v5, v5 quad_perm:[3,2,1,0] row_mask:0xf bank_mask:0xf
	v_cndmask_b32_e64 v4, v251, v250, s[52:53]
	s_nop 1
	v_max_u32_dpp v250, v4, v4 quad_perm:[1,0,3,2] row_mask:0xf bank_mask:0xf
	v_min_u32_dpp v251, v4, v4 quad_perm:[1,0,3,2] row_mask:0xf bank_mask:0xf
	v_cndmask_b32_e64 v5, v251, v250, s[50:51]
	s_nop 1
	v_max_u32_dpp v4, v5, v5 row_half_mirror row_mask:0xf bank_mask:0x5
	v_min_u32_dpp v4, v5, v5 row_half_mirror row_mask:0xf bank_mask:0xa
	s_nop 1
	v_max_u32_dpp v250, v4, v4 quad_perm:[2,3,0,1] row_mask:0xf bank_mask:0xf
	v_min_u32_dpp v251, v4, v4 quad_perm:[2,3,0,1] row_mask:0xf bank_mask:0xf
	v_cndmask_b32_e64 v5, v251, v250, s[52:53]
	s_nop 1
	v_max_u32_dpp v250, v5, v5 quad_perm:[1,0,3,2] row_mask:0xf bank_mask:0xf
	v_min_u32_dpp v251, v5, v5 quad_perm:[1,0,3,2] row_mask:0xf bank_mask:0xf
	v_cndmask_b32_e64 v4, v251, v250, s[50:51]
	s_nop 1
	v_max_u32_dpp v5, v4, v4 row_mirror row_mask:0xf bank_mask:0x3
	v_min_u32_dpp v5, v4, v4 row_mirror row_mask:0xf bank_mask:0xc
	s_nop 1
	v_max_u32_dpp v4, v5, v5 row_ror:12 row_mask:0xf bank_mask:0x5
	v_min_u32_dpp v4, v5, v5 row_ror:4 row_mask:0xf bank_mask:0xa
	s_nop 1
	v_max_u32_dpp v250, v4, v4 quad_perm:[2,3,0,1] row_mask:0xf bank_mask:0xf
	v_min_u32_dpp v251, v4, v4 quad_perm:[2,3,0,1] row_mask:0xf bank_mask:0xf
	v_cndmask_b32_e64 v5, v251, v250, s[52:53]
	s_nop 1
	v_max_u32_dpp v250, v5, v5 quad_perm:[1,0,3,2] row_mask:0xf bank_mask:0xf
	v_min_u32_dpp v251, v5, v5 quad_perm:[1,0,3,2] row_mask:0xf bank_mask:0xf
	v_cndmask_b32_e64 v4, v251, v250, s[50:51]
	ds_swizzle_b32 v252, v4 offset:0x7c1f
	s_waitcnt lgkmcnt(0)
	v_max_u32_dpp v5, v252, v4 quad_perm:[0,1,2,3] row_mask:0x5 bank_mask:0xf
	v_min_u32_dpp v5, v252, v4 quad_perm:[0,1,2,3] row_mask:0xa bank_mask:0xf
	s_nop 1
	v_max_u32_dpp v4, v5, v5 row_ror:8 row_mask:0xf bank_mask:0x3
	v_min_u32_dpp v4, v5, v5 row_ror:8 row_mask:0xf bank_mask:0xc
	s_nop 1
	v_max_u32_dpp v5, v4, v4 row_ror:12 row_mask:0xf bank_mask:0x5
	v_min_u32_dpp v5, v4, v4 row_ror:4 row_mask:0xf bank_mask:0xa
	s_nop 1
	v_max_u32_dpp v250, v5, v5 quad_perm:[2,3,0,1] row_mask:0xf bank_mask:0xf
	v_min_u32_dpp v251, v5, v5 quad_perm:[2,3,0,1] row_mask:0xf bank_mask:0xf
	v_cndmask_b32_e64 v4, v251, v250, s[52:53]
	s_nop 1
	v_max_u32_dpp v250, v4, v4 quad_perm:[1,0,3,2] row_mask:0xf bank_mask:0xf
	v_min_u32_dpp v251, v4, v4 quad_perm:[1,0,3,2] row_mask:0xf bank_mask:0xf
	v_cndmask_b32_e64 v5, v251, v250, s[50:51]
	v_xor_b32_e32 v253, 63, v81
	v_lshlrev_b32_e32 v253, 2, v253
	ds_bpermute_b32 v252, v253, v5
	s_waitcnt lgkmcnt(0)
	v_max_u32_dpp v4, v252, v5 quad_perm:[0,1,2,3] row_mask:0x3 bank_mask:0xf
	v_min_u32_dpp v4, v252, v5 quad_perm:[0,1,2,3] row_mask:0xc bank_mask:0xf
	ds_swizzle_b32 v252, v4 offset:0x401f
	s_waitcnt lgkmcnt(0)
	v_max_u32_dpp v5, v252, v4 quad_perm:[0,1,2,3] row_mask:0x5 bank_mask:0xf
	v_min_u32_dpp v5, v252, v4 quad_perm:[0,1,2,3] row_mask:0xa bank_mask:0xf
	s_nop 1
	v_max_u32_dpp v4, v5, v5 row_ror:8 row_mask:0xf bank_mask:0x3
	v_min_u32_dpp v4, v5, v5 row_ror:8 row_mask:0xf bank_mask:0xc
	s_nop 1
	v_max_u32_dpp v5, v4, v4 row_ror:12 row_mask:0xf bank_mask:0x5
	v_min_u32_dpp v5, v4, v4 row_ror:4 row_mask:0xf bank_mask:0xa
	s_nop 1
	v_max_u32_dpp v250, v5, v5 quad_perm:[2,3,0,1] row_mask:0xf bank_mask:0xf
	v_min_u32_dpp v251, v5, v5 quad_perm:[2,3,0,1] row_mask:0xf bank_mask:0xf
	v_cndmask_b32_e64 v4, v251, v250, s[52:53]
	s_nop 1
	v_max_u32_dpp v250, v4, v4 quad_perm:[1,0,3,2] row_mask:0xf bank_mask:0xf
	v_min_u32_dpp v251, v4, v4 quad_perm:[1,0,3,2] row_mask:0xf bank_mask:0xf
	v_cndmask_b32_e64 v5, v251, v250, s[50:51]
	v_not_b32_e32 v253, v5
	v_and_b32_e32 v253, 63, v253
	v_lshlrev_b32_e32 v253, 2, v253
	ds_permute_b32 v4, v253, v81
	s_waitcnt lgkmcnt(0)
	v_lshlrev_b32_e32 v11, 3, v4
	v_lshlrev_b32_e32 v5, 7, v4
	v_and_b32_e32 v11, 0x70, v11
	v_and_or_b32 v5, v5, s43, v11
	v_cmp_gt_u32_e32 vcc, 16, v4
	ds_permute_b32 v4, v6, v7
	s_nop 0
	v_cndmask_b32_e32 v11, 4, v5, vcc
	ds_permute_b32 v1, v11, v1
	s_waitcnt lgkmcnt(2)
	v_add_f32_e32 v5, v8, v10
	v_div_scale_f32 v8, s[2:3], v5, v5, v9
	v_rcp_f32_e32 v10, v8
	s_waitcnt lgkmcnt(0)
	v_readlane_b32 s2, v1, 0
	v_div_scale_f32 v7, vcc, v9, v5, v9
	s_nop 0
	v_subrev_f32_e32 v1, s2, v1
	v_mul_f32_e32 v1, 0x3fb8aa3b, v1
	v_exp_f32_e32 v1, v1
	v_fma_f32 v6, -v8, v10, 1.0
	v_fmac_f32_e32 v10, v6, v10
	v_mul_f32_e32 v12, v7, v10
	v_cndmask_b32_e64 v1, 0, v1, s[12:13]
	ds_bpermute_b32 v6, v240, v1
	v_fma_f32 v13, -v8, v12, v7
	v_fmac_f32_e32 v12, v13, v10
	v_fma_f32 v7, -v8, v12, v7
	v_div_fmas_f32 v7, v7, v10, v12
	s_waitcnt lgkmcnt(0)
	v_add_f32_e32 v6, v1, v6
	ds_bpermute_b32 v14, v241, v6
	v_div_fixup_f32 v5, v7, v5, v9
	ds_write2st64_b64 v239, v[2:3], v[4:5] offset0:2 offset1:3
	v_not_b32_e32 v7, v0
	v_cmp_gt_i32_e32 vcc, 0, v0
	s_waitcnt lgkmcnt(1)
	v_add_f32_e32 v6, v6, v14
	ds_bpermute_b32 v8, v242, v6
	v_lshlrev_b32_e32 v2, 7, v22
	v_and_b32_e32 v3, 0x7f, v30
	v_and_or_b32 v2, v2, s44, v3
	v_lshlrev_b32_e32 v3, 7, v24
	s_waitcnt lgkmcnt(0)
	v_add_f32_e32 v4, v6, v8
	v_or_b32_e32 v6, 0x80000000, v0
	v_cndmask_b32_e32 v6, v6, v7, vcc
	v_and_b32_e32 v6, 0xffffffc0, v6
	v_cndmask_b32_e64 v6, 0, v6, s[10:11]
	v_bitop3_b32 v6, v6, 63, v81 bitop3:0x36
	ds_bpermute_b32 v5, v243, v4
	s_nop 1
	s_waitcnt lgkmcnt(0)
	v_max_u32_dpp v250, v6, v6 quad_perm:[1,0,3,2] row_mask:0xf bank_mask:0xf
	v_add_f32_e32 v4, v4, v5
	v_min_u32_dpp v251, v6, v6 quad_perm:[1,0,3,2] row_mask:0xf bank_mask:0xf
	v_cndmask_b32_e64 v7, v251, v250, s[50:51]
	s_nop 1
	v_max_u32_dpp v250, v7, v7 quad_perm:[3,2,1,0] row_mask:0xf bank_mask:0xf
	v_min_u32_dpp v251, v7, v7 quad_perm:[3,2,1,0] row_mask:0xf bank_mask:0xf
	v_cndmask_b32_e64 v6, v251, v250, s[52:53]
	s_nop 1
	v_max_u32_dpp v250, v6, v6 quad_perm:[1,0,3,2] row_mask:0xf bank_mask:0xf
	v_min_u32_dpp v251, v6, v6 quad_perm:[1,0,3,2] row_mask:0xf bank_mask:0xf
	v_cndmask_b32_e64 v7, v251, v250, s[50:51]
	s_nop 1
	v_max_u32_dpp v6, v7, v7 row_half_mirror row_mask:0xf bank_mask:0x5
	v_min_u32_dpp v6, v7, v7 row_half_mirror row_mask:0xf bank_mask:0xa
	s_nop 1
	v_max_u32_dpp v250, v6, v6 quad_perm:[2,3,0,1] row_mask:0xf bank_mask:0xf
	v_min_u32_dpp v251, v6, v6 quad_perm:[2,3,0,1] row_mask:0xf bank_mask:0xf
	v_cndmask_b32_e64 v7, v251, v250, s[52:53]
	s_nop 1
	v_max_u32_dpp v250, v7, v7 quad_perm:[1,0,3,2] row_mask:0xf bank_mask:0xf
	v_min_u32_dpp v251, v7, v7 quad_perm:[1,0,3,2] row_mask:0xf bank_mask:0xf
	v_cndmask_b32_e64 v6, v251, v250, s[50:51]
	s_nop 1
	v_max_u32_dpp v7, v6, v6 row_mirror row_mask:0xf bank_mask:0x3
	v_min_u32_dpp v7, v6, v6 row_mirror row_mask:0xf bank_mask:0xc
	s_nop 1
	v_max_u32_dpp v6, v7, v7 row_ror:12 row_mask:0xf bank_mask:0x5
	v_min_u32_dpp v6, v7, v7 row_ror:4 row_mask:0xf bank_mask:0xa
	s_nop 1
	v_max_u32_dpp v250, v6, v6 quad_perm:[2,3,0,1] row_mask:0xf bank_mask:0xf
	v_min_u32_dpp v251, v6, v6 quad_perm:[2,3,0,1] row_mask:0xf bank_mask:0xf
	v_cndmask_b32_e64 v7, v251, v250, s[52:53]
	s_nop 1
	v_max_u32_dpp v250, v7, v7 quad_perm:[1,0,3,2] row_mask:0xf bank_mask:0xf
	v_min_u32_dpp v251, v7, v7 quad_perm:[1,0,3,2] row_mask:0xf bank_mask:0xf
	v_cndmask_b32_e64 v6, v251, v250, s[50:51]
	ds_swizzle_b32 v252, v6 offset:0x7c1f
	s_waitcnt lgkmcnt(0)
	v_max_u32_dpp v7, v252, v6 quad_perm:[0,1,2,3] row_mask:0x5 bank_mask:0xf
	v_min_u32_dpp v7, v252, v6 quad_perm:[0,1,2,3] row_mask:0xa bank_mask:0xf
	s_nop 1
	v_max_u32_dpp v6, v7, v7 row_ror:8 row_mask:0xf bank_mask:0x3
	v_min_u32_dpp v6, v7, v7 row_ror:8 row_mask:0xf bank_mask:0xc
	s_nop 1
	v_max_u32_dpp v7, v6, v6 row_ror:12 row_mask:0xf bank_mask:0x5
	v_min_u32_dpp v7, v6, v6 row_ror:4 row_mask:0xf bank_mask:0xa
	s_nop 1
	v_max_u32_dpp v250, v7, v7 quad_perm:[2,3,0,1] row_mask:0xf bank_mask:0xf
	v_min_u32_dpp v251, v7, v7 quad_perm:[2,3,0,1] row_mask:0xf bank_mask:0xf
	v_cndmask_b32_e64 v6, v251, v250, s[52:53]
	s_nop 1
	v_max_u32_dpp v250, v6, v6 quad_perm:[1,0,3,2] row_mask:0xf bank_mask:0xf
	v_min_u32_dpp v251, v6, v6 quad_perm:[1,0,3,2] row_mask:0xf bank_mask:0xf
	v_cndmask_b32_e64 v7, v251, v250, s[50:51]
	v_xor_b32_e32 v253, 63, v81
	v_lshlrev_b32_e32 v253, 2, v253
	ds_bpermute_b32 v252, v253, v7
	s_waitcnt lgkmcnt(0)
	v_max_u32_dpp v6, v252, v7 quad_perm:[0,1,2,3] row_mask:0x3 bank_mask:0xf
	v_min_u32_dpp v6, v252, v7 quad_perm:[0,1,2,3] row_mask:0xc bank_mask:0xf
	ds_swizzle_b32 v252, v6 offset:0x401f
	s_waitcnt lgkmcnt(0)
	v_max_u32_dpp v7, v252, v6 quad_perm:[0,1,2,3] row_mask:0x5 bank_mask:0xf
	v_min_u32_dpp v7, v252, v6 quad_perm:[0,1,2,3] row_mask:0xa bank_mask:0xf
	s_nop 1
	v_max_u32_dpp v6, v7, v7 row_ror:8 row_mask:0xf bank_mask:0x3
	v_min_u32_dpp v6, v7, v7 row_ror:8 row_mask:0xf bank_mask:0xc
	s_nop 1
	v_max_u32_dpp v7, v6, v6 row_ror:12 row_mask:0xf bank_mask:0x5
	v_min_u32_dpp v7, v6, v6 row_ror:4 row_mask:0xf bank_mask:0xa
	s_nop 1
	v_max_u32_dpp v250, v7, v7 quad_perm:[2,3,0,1] row_mask:0xf bank_mask:0xf
	v_min_u32_dpp v251, v7, v7 quad_perm:[2,3,0,1] row_mask:0xf bank_mask:0xf
	v_cndmask_b32_e64 v6, v251, v250, s[52:53]
	s_nop 1
	v_max_u32_dpp v250, v6, v6 quad_perm:[1,0,3,2] row_mask:0xf bank_mask:0xf
	v_min_u32_dpp v251, v6, v6 quad_perm:[1,0,3,2] row_mask:0xf bank_mask:0xf
	v_cndmask_b32_e64 v7, v251, v250, s[50:51]
	v_not_b32_e32 v253, v7
	v_and_b32_e32 v253, 63, v253
	v_lshlrev_b32_e32 v253, 2, v253
	ds_permute_b32 v6, v253, v81
	s_waitcnt lgkmcnt(0)
	v_lshlrev_b32_e32 v8, 3, v6
	v_lshlrev_b32_e32 v7, 7, v6
	v_and_b32_e32 v8, 0x70, v8
	v_and_or_b32 v7, v7, s43, v8
	v_cmp_gt_u32_e32 vcc, 16, v6
	s_nop 1
	v_cndmask_b32_e32 v6, 4, v7, vcc
	ds_permute_b32 v0, v6, v0
	v_and_b32_e32 v7, 0x7f, v29
	v_and_or_b32 v7, v3, s44, v7
	s_waitcnt lgkmcnt(0)
	v_readlane_b32 s2, v0, 0
	s_nop 1
	v_subrev_f32_e32 v0, s2, v0
	v_mul_f32_e32 v0, 0x3fb8aa3b, v0
	v_exp_f32_e32 v5, v0
	ds_permute_b32 v0, v11, v2
	v_div_scale_f32 v8, s[2:3], v4, v4, v1
	v_cndmask_b32_e64 v10, 0, v5, s[12:13]
	ds_bpermute_b32 v2, v240, v10
	v_rcp_f32_e32 v9, v8
	s_waitcnt lgkmcnt(0)
	v_add_f32_e32 v2, v10, v2
	ds_bpermute_b32 v11, v241, v2
	v_fma_f32 v5, -v8, v9, 1.0
	v_fmac_f32_e32 v9, v5, v9
	v_div_scale_f32 v5, vcc, v1, v4, v1
	v_mul_f32_e32 v12, v5, v9
	v_fma_f32 v13, -v8, v12, v5
	v_fmac_f32_e32 v12, v13, v9
	s_waitcnt lgkmcnt(0)
	v_add_f32_e32 v2, v2, v11
	v_fma_f32 v5, -v8, v12, v5
	ds_bpermute_b32 v8, v242, v2
	v_div_fmas_f32 v5, v5, v9, v12
	s_waitcnt vmcnt(25)
	v_cmp_lt_i32_e32 vcc, -1, v19
	v_div_fixup_f32 v1, v5, v4, v1
	v_and_b32_e32 v4, 0xffffff80, v20
	v_cndmask_b32_e64 v3, v232, -1, vcc
	v_cmp_lt_i32_e32 vcc, -1, v20
	s_waitcnt lgkmcnt(0)
	v_add_f32_e32 v8, v2, v8
	v_and_b32_e32 v2, 0xffffff80, v19
	v_cndmask_b32_e64 v5, v232, -1, vcc
	s_waitcnt vmcnt(24)
	v_cmp_lt_i32_e32 vcc, -1, v16
	v_xor_b32_e32 v3, v3, v2
	v_xor_b32_e32 v5, v5, v4
	v_cndmask_b32_e64 v11, v232, -1, vcc
	v_cmp_lt_i32_e32 vcc, -1, v18
	v_and_b32_e32 v2, 0xffffff80, v16
	v_and_b32_e32 v4, 0xffffff80, v18
	v_cndmask_b32_e64 v12, v232, -1, vcc
	v_xor_b32_e32 v2, v11, v2
	v_xor_b32_e32 v4, v12, v4
	v_pk_add_f32 v[2:3], v[4:5], v[2:3]
	ds_bpermute_b32 v9, v243, v8
	v_or_b32_e32 v4, 0x80000000, v3
	v_not_b32_e32 v5, v3
	v_cmp_gt_i32_e32 vcc, 0, v3
	s_nop 1
	v_cndmask_b32_e32 v4, v4, v5, vcc
	v_and_b32_e32 v4, 0xffffffc0, v4
	v_cndmask_b32_e64 v4, 0, v4, s[10:11]
	v_bitop3_b32 v4, v4, 63, v81 bitop3:0x36
	s_nop 0
	s_nop 1
	v_max_u32_dpp v250, v4, v4 quad_perm:[1,0,3,2] row_mask:0xf bank_mask:0xf
	v_min_u32_dpp v251, v4, v4 quad_perm:[1,0,3,2] row_mask:0xf bank_mask:0xf
	v_cndmask_b32_e64 v5, v251, v250, s[50:51]
	s_nop 1
	v_max_u32_dpp v250, v5, v5 quad_perm:[3,2,1,0] row_mask:0xf bank_mask:0xf
	v_min_u32_dpp v251, v5, v5 quad_perm:[3,2,1,0] row_mask:0xf bank_mask:0xf
	v_cndmask_b32_e64 v4, v251, v250, s[52:53]
	s_nop 1
	v_max_u32_dpp v250, v4, v4 quad_perm:[1,0,3,2] row_mask:0xf bank_mask:0xf
	v_min_u32_dpp v251, v4, v4 quad_perm:[1,0,3,2] row_mask:0xf bank_mask:0xf
	v_cndmask_b32_e64 v5, v251, v250, s[50:51]
	s_nop 1
	v_max_u32_dpp v4, v5, v5 row_half_mirror row_mask:0xf bank_mask:0x5
	v_min_u32_dpp v4, v5, v5 row_half_mirror row_mask:0xf bank_mask:0xa
	s_nop 1
	v_max_u32_dpp v250, v4, v4 quad_perm:[2,3,0,1] row_mask:0xf bank_mask:0xf
	v_min_u32_dpp v251, v4, v4 quad_perm:[2,3,0,1] row_mask:0xf bank_mask:0xf
	v_cndmask_b32_e64 v5, v251, v250, s[52:53]
	s_nop 1
	v_max_u32_dpp v250, v5, v5 quad_perm:[1,0,3,2] row_mask:0xf bank_mask:0xf
	v_min_u32_dpp v251, v5, v5 quad_perm:[1,0,3,2] row_mask:0xf bank_mask:0xf
	v_cndmask_b32_e64 v4, v251, v250, s[50:51]
	s_nop 1
	v_max_u32_dpp v5, v4, v4 row_mirror row_mask:0xf bank_mask:0x3
	v_min_u32_dpp v5, v4, v4 row_mirror row_mask:0xf bank_mask:0xc
	s_nop 1
	v_max_u32_dpp v4, v5, v5 row_ror:12 row_mask:0xf bank_mask:0x5
	v_min_u32_dpp v4, v5, v5 row_ror:4 row_mask:0xf bank_mask:0xa
	s_nop 1
	v_max_u32_dpp v250, v4, v4 quad_perm:[2,3,0,1] row_mask:0xf bank_mask:0xf
	v_min_u32_dpp v251, v4, v4 quad_perm:[2,3,0,1] row_mask:0xf bank_mask:0xf
	v_cndmask_b32_e64 v5, v251, v250, s[52:53]
	s_nop 1
	v_max_u32_dpp v250, v5, v5 quad_perm:[1,0,3,2] row_mask:0xf bank_mask:0xf
	v_min_u32_dpp v251, v5, v5 quad_perm:[1,0,3,2] row_mask:0xf bank_mask:0xf
	v_cndmask_b32_e64 v4, v251, v250, s[50:51]
	ds_swizzle_b32 v252, v4 offset:0x7c1f
	s_waitcnt lgkmcnt(0)
	v_max_u32_dpp v5, v252, v4 quad_perm:[0,1,2,3] row_mask:0x5 bank_mask:0xf
	v_min_u32_dpp v5, v252, v4 quad_perm:[0,1,2,3] row_mask:0xa bank_mask:0xf
	s_nop 1
	v_max_u32_dpp v4, v5, v5 row_ror:8 row_mask:0xf bank_mask:0x3
	v_min_u32_dpp v4, v5, v5 row_ror:8 row_mask:0xf bank_mask:0xc
	s_nop 1
	v_max_u32_dpp v5, v4, v4 row_ror:12 row_mask:0xf bank_mask:0x5
	v_min_u32_dpp v5, v4, v4 row_ror:4 row_mask:0xf bank_mask:0xa
	s_nop 1
	v_max_u32_dpp v250, v5, v5 quad_perm:[2,3,0,1] row_mask:0xf bank_mask:0xf
	v_min_u32_dpp v251, v5, v5 quad_perm:[2,3,0,1] row_mask:0xf bank_mask:0xf
	v_cndmask_b32_e64 v4, v251, v250, s[52:53]
	s_nop 1
	v_max_u32_dpp v250, v4, v4 quad_perm:[1,0,3,2] row_mask:0xf bank_mask:0xf
	v_min_u32_dpp v251, v4, v4 quad_perm:[1,0,3,2] row_mask:0xf bank_mask:0xf
	v_cndmask_b32_e64 v5, v251, v250, s[50:51]
	v_xor_b32_e32 v253, 63, v81
	v_lshlrev_b32_e32 v253, 2, v253
	ds_bpermute_b32 v252, v253, v5
	s_waitcnt lgkmcnt(0)
	v_max_u32_dpp v4, v252, v5 quad_perm:[0,1,2,3] row_mask:0x3 bank_mask:0xf
	v_min_u32_dpp v4, v252, v5 quad_perm:[0,1,2,3] row_mask:0xc bank_mask:0xf
	ds_swizzle_b32 v252, v4 offset:0x401f
	s_waitcnt lgkmcnt(0)
	v_max_u32_dpp v5, v252, v4 quad_perm:[0,1,2,3] row_mask:0x5 bank_mask:0xf
	v_min_u32_dpp v5, v252, v4 quad_perm:[0,1,2,3] row_mask:0xa bank_mask:0xf
	s_nop 1
	v_max_u32_dpp v4, v5, v5 row_ror:8 row_mask:0xf bank_mask:0x3
	v_min_u32_dpp v4, v5, v5 row_ror:8 row_mask:0xf bank_mask:0xc
	s_nop 1
	v_max_u32_dpp v5, v4, v4 row_ror:12 row_mask:0xf bank_mask:0x5
	v_min_u32_dpp v5, v4, v4 row_ror:4 row_mask:0xf bank_mask:0xa
	s_nop 1
	v_max_u32_dpp v250, v5, v5 quad_perm:[2,3,0,1] row_mask:0xf bank_mask:0xf
	v_min_u32_dpp v251, v5, v5 quad_perm:[2,3,0,1] row_mask:0xf bank_mask:0xf
	v_cndmask_b32_e64 v4, v251, v250, s[52:53]
	s_nop 1
	v_max_u32_dpp v250, v4, v4 quad_perm:[1,0,3,2] row_mask:0xf bank_mask:0xf
	v_min_u32_dpp v251, v4, v4 quad_perm:[1,0,3,2] row_mask:0xf bank_mask:0xf
	v_cndmask_b32_e64 v5, v251, v250, s[50:51]
	v_not_b32_e32 v253, v5
	v_and_b32_e32 v253, 63, v253
	v_lshlrev_b32_e32 v253, 2, v253
	ds_permute_b32 v4, v253, v81
	s_waitcnt lgkmcnt(0)
	v_lshlrev_b32_e32 v11, 3, v4
	v_lshlrev_b32_e32 v5, 7, v4
	v_and_b32_e32 v11, 0x70, v11
	v_and_or_b32 v5, v5, s43, v11
	v_cmp_gt_u32_e32 vcc, 16, v4
	ds_permute_b32 v4, v6, v7
	s_nop 0
	v_cndmask_b32_e32 v11, 4, v5, vcc
	s_waitcnt lgkmcnt(1)
	v_add_f32_e32 v5, v8, v9
	v_div_scale_f32 v8, s[2:3], v5, v5, v10
	v_rcp_f32_e32 v9, v8
	v_div_scale_f32 v7, vcc, v10, v5, v10
	ds_permute_b32 v3, v11, v3
	v_fma_f32 v6, -v8, v9, 1.0
	v_fmac_f32_e32 v9, v6, v9
	v_mul_f32_e32 v12, v7, v9
	v_fma_f32 v13, -v8, v12, v7
	v_fmac_f32_e32 v12, v13, v9
	v_fma_f32 v7, -v8, v12, v7
	v_div_fmas_f32 v7, v7, v9, v12
	v_or_b32_e32 v8, 0x80000000, v2
	v_not_b32_e32 v9, v2
	v_cmp_gt_i32_e32 vcc, 0, v2
	s_waitcnt lgkmcnt(0)
	v_readlane_b32 s2, v3, 0
	v_div_fixup_f32 v5, v7, v5, v10
	v_cndmask_b32_e32 v8, v8, v9, vcc
	v_and_b32_e32 v8, 0xffffffc0, v8
	v_cndmask_b32_e64 v8, 0, v8, s[10:11]
	v_bitop3_b32 v8, v8, 63, v81 bitop3:0x36
	v_subrev_f32_e32 v3, s2, v3
	s_nop 1
	v_mul_f32_e32 v3, 0x3fb8aa3b, v3
	v_exp_f32_e32 v3, v3
	v_max_u32_dpp v250, v8, v8 quad_perm:[1,0,3,2] row_mask:0xf bank_mask:0xf
	v_min_u32_dpp v251, v8, v8 quad_perm:[1,0,3,2] row_mask:0xf bank_mask:0xf
	v_cndmask_b32_e64 v9, v251, v250, s[50:51]
	ds_write2st64_b64 v239, v[0:1], v[4:5] offset0:4 offset1:5
	s_nop 1
	v_max_u32_dpp v250, v9, v9 quad_perm:[3,2,1,0] row_mask:0xf bank_mask:0xf
	v_min_u32_dpp v251, v9, v9 quad_perm:[3,2,1,0] row_mask:0xf bank_mask:0xf
	v_cndmask_b32_e64 v3, 0, v3, s[12:13]
	v_cndmask_b32_e64 v8, v251, v250, s[52:53]
	s_nop 1
	v_max_u32_dpp v250, v8, v8 quad_perm:[1,0,3,2] row_mask:0xf bank_mask:0xf
	ds_bpermute_b32 v6, v240, v3
	v_min_u32_dpp v251, v8, v8 quad_perm:[1,0,3,2] row_mask:0xf bank_mask:0xf
	v_cndmask_b32_e64 v9, v251, v250, s[50:51]
	s_nop 1
	v_lshlrev_b32_e32 v0, 7, v20
	v_max_u32_dpp v8, v9, v9 row_half_mirror row_mask:0xf bank_mask:0x5
	v_min_u32_dpp v8, v9, v9 row_half_mirror row_mask:0xf bank_mask:0xa
	s_nop 1
	s_waitcnt lgkmcnt(0)
	v_add_f32_e32 v6, v3, v6
	v_max_u32_dpp v250, v8, v8 quad_perm:[2,3,0,1] row_mask:0xf bank_mask:0xf
	v_min_u32_dpp v251, v8, v8 quad_perm:[2,3,0,1] row_mask:0xf bank_mask:0xf
	v_cndmask_b32_e64 v9, v251, v250, s[52:53]
	ds_bpermute_b32 v13, v241, v6
	s_nop 1
	v_max_u32_dpp v250, v9, v9 quad_perm:[1,0,3,2] row_mask:0xf bank_mask:0xf
	v_min_u32_dpp v251, v9, v9 quad_perm:[1,0,3,2] row_mask:0xf bank_mask:0xf
	s_waitcnt lgkmcnt(0)
	v_cndmask_b32_e64 v8, v251, v250, s[50:51]
	v_add_f32_e32 v6, v6, v13
	s_nop 1
	v_max_u32_dpp v9, v8, v8 row_mirror row_mask:0xf bank_mask:0x3
	v_min_u32_dpp v9, v8, v8 row_mirror row_mask:0xf bank_mask:0xc
	ds_bpermute_b32 v7, v242, v6
	s_nop 1
	v_max_u32_dpp v8, v9, v9 row_ror:12 row_mask:0xf bank_mask:0x5
	v_min_u32_dpp v8, v9, v9 row_ror:4 row_mask:0xf bank_mask:0xa
	v_and_b32_e32 v1, 0x7f, v19
	s_nop 1
	v_max_u32_dpp v250, v8, v8 quad_perm:[2,3,0,1] row_mask:0xf bank_mask:0xf
	v_min_u32_dpp v251, v8, v8 quad_perm:[2,3,0,1] row_mask:0xf bank_mask:0xf
	s_waitcnt lgkmcnt(0)
	v_cndmask_b32_e64 v9, v251, v250, s[52:53]
	v_add_f32_e32 v4, v6, v7
	s_nop 1
	v_max_u32_dpp v250, v9, v9 quad_perm:[1,0,3,2] row_mask:0xf bank_mask:0xf
	v_min_u32_dpp v251, v9, v9 quad_perm:[1,0,3,2] row_mask:0xf bank_mask:0xf
	v_and_or_b32 v0, v0, s44, v1
	v_cndmask_b32_e64 v8, v251, v250, s[50:51]
	ds_swizzle_b32 v252, v8 offset:0x7c1f
	s_waitcnt lgkmcnt(0)
	ds_bpermute_b32 v5, v243, v4
	v_max_u32_dpp v9, v252, v8 quad_perm:[0,1,2,3] row_mask:0x5 bank_mask:0xf
	v_min_u32_dpp v9, v252, v8 quad_perm:[0,1,2,3] row_mask:0xa bank_mask:0xf
	s_nop 1
	ds_permute_b32 v0, v11, v0
	v_max_u32_dpp v8, v9, v9 row_ror:8 row_mask:0xf bank_mask:0x3
	v_min_u32_dpp v8, v9, v9 row_ror:8 row_mask:0xf bank_mask:0xc
	v_lshlrev_b32_e32 v6, 7, v18
	s_nop 1
	v_max_u32_dpp v9, v8, v8 row_ror:12 row_mask:0xf bank_mask:0x5
	v_min_u32_dpp v9, v8, v8 row_ror:4 row_mask:0xf bank_mask:0xa
	s_nop 1
	v_max_u32_dpp v250, v9, v9 quad_perm:[2,3,0,1] row_mask:0xf bank_mask:0xf
	v_min_u32_dpp v251, v9, v9 quad_perm:[2,3,0,1] row_mask:0xf bank_mask:0xf
	v_cndmask_b32_e64 v8, v251, v250, s[52:53]
	s_nop 1
	v_max_u32_dpp v250, v8, v8 quad_perm:[1,0,3,2] row_mask:0xf bank_mask:0xf
	v_min_u32_dpp v251, v8, v8 quad_perm:[1,0,3,2] row_mask:0xf bank_mask:0xf
	v_cndmask_b32_e64 v9, v251, v250, s[50:51]
	v_xor_b32_e32 v253, 63, v81
	v_lshlrev_b32_e32 v253, 2, v253
	ds_bpermute_b32 v252, v253, v9
	s_waitcnt lgkmcnt(0)
	v_max_u32_dpp v8, v252, v9 quad_perm:[0,1,2,3] row_mask:0x3 bank_mask:0xf
	v_min_u32_dpp v8, v252, v9 quad_perm:[0,1,2,3] row_mask:0xc bank_mask:0xf
	ds_swizzle_b32 v252, v8 offset:0x401f
	s_waitcnt lgkmcnt(0)
	v_max_u32_dpp v9, v252, v8 quad_perm:[0,1,2,3] row_mask:0x5 bank_mask:0xf
	v_min_u32_dpp v9, v252, v8 quad_perm:[0,1,2,3] row_mask:0xa bank_mask:0xf
	s_nop 1
	v_max_u32_dpp v8, v9, v9 row_ror:8 row_mask:0xf bank_mask:0x3
	v_min_u32_dpp v8, v9, v9 row_ror:8 row_mask:0xf bank_mask:0xc
	s_nop 1
	v_max_u32_dpp v9, v8, v8 row_ror:12 row_mask:0xf bank_mask:0x5
	v_min_u32_dpp v9, v8, v8 row_ror:4 row_mask:0xf bank_mask:0xa
	s_nop 1
	v_max_u32_dpp v250, v9, v9 quad_perm:[2,3,0,1] row_mask:0xf bank_mask:0xf
	v_min_u32_dpp v251, v9, v9 quad_perm:[2,3,0,1] row_mask:0xf bank_mask:0xf
	v_cndmask_b32_e64 v8, v251, v250, s[52:53]
	s_nop 1
	v_max_u32_dpp v250, v8, v8 quad_perm:[1,0,3,2] row_mask:0xf bank_mask:0xf
	v_min_u32_dpp v251, v8, v8 quad_perm:[1,0,3,2] row_mask:0xf bank_mask:0xf
	v_cndmask_b32_e64 v9, v251, v250, s[50:51]
	v_not_b32_e32 v253, v9
	v_and_b32_e32 v253, 63, v253
	v_lshlrev_b32_e32 v253, 2, v253
	ds_permute_b32 v8, v253, v81
	s_waitcnt lgkmcnt(0)
	v_lshlrev_b32_e32 v10, 3, v8
	v_lshlrev_b32_e32 v9, 7, v8
	v_and_b32_e32 v10, 0x70, v10
	v_and_or_b32 v9, v9, s43, v10
	v_cmp_gt_u32_e32 vcc, 16, v8
	v_and_b32_e32 v10, 0x7f, v16
	s_nop 0
	v_cndmask_b32_e32 v8, 4, v9, vcc
	ds_permute_b32 v2, v8, v2
	s_waitcnt lgkmcnt(0)
	v_readlane_b32 s2, v2, 0
	s_nop 1
	v_subrev_f32_e32 v2, s2, v2
	v_mul_f32_e32 v2, 0x3fb8aa3b, v2
	v_exp_f32_e32 v2, v2
	s_nop 0
	v_cndmask_b32_e64 v7, 0, v2, s[12:13]
	ds_bpermute_b32 v1, v240, v7
	v_add_f32_e32 v2, v4, v5
	v_div_scale_f32 v4, s[2:3], v2, v2, v3
	v_rcp_f32_e32 v5, v4
	s_waitcnt lgkmcnt(0)
	v_add_f32_e32 v1, v7, v1
	ds_bpermute_b32 v9, v241, v1
	v_fma_f32 v11, -v4, v5, 1.0
	v_fmac_f32_e32 v5, v11, v5
	v_div_scale_f32 v11, vcc, v3, v2, v3
	s_waitcnt lgkmcnt(0)
	v_add_f32_e32 v1, v1, v9
	ds_bpermute_b32 v9, v242, v1
	v_mul_f32_e32 v12, v11, v5
	v_fma_f32 v13, -v4, v12, v11
	v_fmac_f32_e32 v12, v13, v5
	v_fma_f32 v4, -v4, v12, v11
	s_waitcnt lgkmcnt(0)
	v_add_f32_e32 v1, v1, v9
	ds_bpermute_b32 v9, v243, v1
	v_div_fmas_f32 v4, v4, v5, v12
	s_waitcnt lgkmcnt(0)
	v_add_f32_e32 v5, v1, v9
	v_div_scale_f32 v9, s[2:3], v5, v5, v7
	v_rcp_f32_e32 v11, v9
	v_div_fixup_f32 v1, v4, v2, v3
	v_and_or_b32 v2, v6, s44, v10
	ds_permute_b32 v2, v8, v2
	v_fma_f32 v3, -v9, v11, 1.0
	v_fmac_f32_e32 v11, v3, v11
	v_div_scale_f32 v3, vcc, v7, v5, v7
	v_mul_f32_e32 v4, v3, v11
	v_fma_f32 v6, -v9, v4, v3
	v_fmac_f32_e32 v4, v6, v11
	v_fma_f32 v3, -v9, v4, v3
	v_div_fmas_f32 v3, v3, v11, v4
	v_div_fixup_f32 v3, v3, v5, v7
	s_waitcnt lgkmcnt(0)
	ds_write2st64_b64 v239, v[0:1], v[2:3] offset0:6 offset1:7
	s_branch .LBB0_330
